# retention scan finalize: the 8-lane row-sum of squares uses three DPP adds (quad_perm, quad_perm, row_half_mirror) instead of three dependent ds_swizzle round trips (bit-identical)
# baseline (speedup 1.0000x reference)
.LBB0_617:
	ds_read_b128 v[164:167], v190
	ds_read_b64_tr_b16 v[126:127], v189 offset:576
	ds_read_b64_tr_b16 v[122:123], v189 offset:5184
	ds_read_b64_tr_b16 v[124:125], v189
	ds_read_b64_tr_b16 v[120:121], v189 offset:4608
	ds_read_b128 v[168:171], v190 offset:2304
	ds_read_b128 v[176:179], v190 offset:4608
	ds_read_b128 v[202:205], v190 offset:6912
	s_waitcnt lgkmcnt(5)
	v_cndmask_b32_e64 v175, v123, v127, s[4:5]
	v_cndmask_b32_e64 v174, v122, v126, s[4:5]
	s_waitcnt lgkmcnt(3)
	v_cndmask_b32_e64 v173, v121, v125, s[4:5]
	v_cndmask_b32_e64 v172, v120, v124, s[4:5]
	s_add_i32 s27, s22, -3
	s_min_u32 s8, s27, 61
	v_mfma_f32_16x16x32_bf16 v[164:167], v[164:167], v[172:175], 0
	s_lshl_b32 s8, s8, 6
	s_addk_i32 s8, 0x80
	s_waitcnt lgkmcnt(2)
	v_mfma_f32_16x16x32_bf16 v[168:171], v[168:171], v[172:175], 0
	s_waitcnt lgkmcnt(1)
	v_mfma_f32_16x16x32_bf16 v[176:179], v[176:179], v[172:175], 0
	s_waitcnt lgkmcnt(0)
	v_mfma_f32_16x16x32_bf16 v[172:175], v[202:205], v[172:175], 0
	s_waitcnt vmcnt(21)
	ds_write_b128 v191, v[0:3] offset:33792
	v_lshl_add_u64 v[0:1], s[8:9], 0, v[134:135]
	v_lshlrev_b64 v[0:1], 11, v[0:1]
	v_lshl_add_u64 v[0:1], v[146:147], 0, v[0:1]
	global_load_dwordx4 v[0:3], v[0:1], off
	ds_read_b128 v[202:205], v192
	ds_read_b128 v[206:209], v192 offset:8448
	v_cvt_pk_bf16_f32 v210, v88, v89
	v_cvt_pk_bf16_f32 v211, v90, v91
	v_cvt_pk_bf16_f32 v212, v92, v93
	v_cvt_pk_bf16_f32 v213, v94, v95
	s_waitcnt lgkmcnt(1)
	s_nop 0
	v_mfma_f32_16x16x32_bf16 v[164:167], v[202:205], v[210:213], v[164:167]
	ds_read_b128 v[202:205], v192 offset:16896
	s_waitcnt lgkmcnt(1)
	v_mfma_f32_16x16x32_bf16 v[168:171], v[206:209], v[210:213], v[168:171]
	ds_read_b128 v[206:209], v192 offset:25344
	s_waitcnt lgkmcnt(1)
	v_mfma_f32_16x16x32_bf16 v[176:179], v[202:205], v[210:213], v[176:179]
	s_waitcnt lgkmcnt(0)
	v_mfma_f32_16x16x32_bf16 v[172:175], v[206:209], v[210:213], v[172:175]
	s_waitcnt vmcnt(21)
	ds_write_b128 v193, v[4:7] offset:33792
	v_lshl_add_u64 v[4:5], s[8:9], 0, v[136:137]
	v_lshlrev_b64 v[4:5], 11, v[4:5]
	v_lshl_add_u64 v[4:5], v[146:147], 0, v[4:5]
	global_load_dwordx4 v[4:7], v[4:5], off
	ds_read_b128 v[202:205], v192 offset:64
	ds_read_b128 v[206:209], v192 offset:8512
	v_cvt_pk_bf16_f32 v210, v96, v97
	v_cvt_pk_bf16_f32 v211, v98, v99
	v_cvt_pk_bf16_f32 v212, v100, v101
	v_cvt_pk_bf16_f32 v213, v102, v103
	s_waitcnt lgkmcnt(1)
	s_nop 0
	v_mfma_f32_16x16x32_bf16 v[164:167], v[202:205], v[210:213], v[164:167]
	ds_read_b128 v[202:205], v192 offset:16960
	s_waitcnt lgkmcnt(1)
	v_mfma_f32_16x16x32_bf16 v[168:171], v[206:209], v[210:213], v[168:171]
	ds_read_b128 v[206:209], v192 offset:25408
	s_waitcnt lgkmcnt(1)
	v_mfma_f32_16x16x32_bf16 v[176:179], v[202:205], v[210:213], v[176:179]
	s_waitcnt lgkmcnt(0)
	v_mfma_f32_16x16x32_bf16 v[172:175], v[206:209], v[210:213], v[172:175]
	s_waitcnt vmcnt(21)
	ds_write_b128 v194, v[8:11] offset:33792
	v_lshl_add_u64 v[8:9], s[8:9], 0, v[138:139]
	v_lshlrev_b64 v[8:9], 11, v[8:9]
	v_lshl_add_u64 v[8:9], v[146:147], 0, v[8:9]
	global_load_dwordx4 v[8:11], v[8:9], off
	ds_read_b128 v[202:205], v192 offset:128
	ds_read_b128 v[206:209], v192 offset:8576
	v_cvt_pk_bf16_f32 v210, v104, v105
	v_cvt_pk_bf16_f32 v211, v106, v107
	v_cvt_pk_bf16_f32 v212, v116, v117
	v_cvt_pk_bf16_f32 v213, v118, v119
	s_waitcnt lgkmcnt(1)
	s_nop 0
	v_mfma_f32_16x16x32_bf16 v[164:167], v[202:205], v[210:213], v[164:167]
	ds_read_b128 v[202:205], v192 offset:17024
	s_waitcnt lgkmcnt(1)
	v_mfma_f32_16x16x32_bf16 v[168:171], v[206:209], v[210:213], v[168:171]
	ds_read_b128 v[206:209], v192 offset:25472
	s_waitcnt lgkmcnt(1)
	v_mfma_f32_16x16x32_bf16 v[176:179], v[202:205], v[210:213], v[176:179]
	s_waitcnt lgkmcnt(0)
	v_mfma_f32_16x16x32_bf16 v[172:175], v[206:209], v[210:213], v[172:175]
	s_waitcnt vmcnt(21)
	ds_write_b128 v195, v[12:15] offset:33792
	v_lshl_add_u64 v[12:13], s[8:9], 0, v[140:141]
	v_lshlrev_b64 v[12:13], 11, v[12:13]
	v_lshl_add_u64 v[12:13], v[146:147], 0, v[12:13]
	global_load_dwordx4 v[12:15], v[12:13], off
	ds_read_b128 v[202:205], v192 offset:192
	ds_read_b128 v[206:209], v192 offset:8640
	v_cvt_pk_bf16_f32 v210, v108, v109
	v_cvt_pk_bf16_f32 v211, v110, v111
	v_cvt_pk_bf16_f32 v212, v112, v113
	v_cvt_pk_bf16_f32 v213, v114, v115
	s_min_u32 s20, s27, 60
	s_lshl_b32 s8, s20, 6
	s_waitcnt lgkmcnt(1)
	v_mfma_f32_16x16x32_bf16 v[164:167], v[202:205], v[210:213], v[164:167]
	ds_read_b128 v[202:205], v192 offset:17088
	s_addk_i32 s8, 0xc0
	s_lshl_b32 s20, s20, 13
	s_waitcnt lgkmcnt(1)
	v_mfma_f32_16x16x32_bf16 v[168:171], v[206:209], v[210:213], v[168:171]
	ds_read_b128 v[206:209], v192 offset:25536
	s_nop 1
	ds_write2_b32 v196, v164, v165 offset1:68
	ds_write2_b32 v196, v166, v167 offset0:136 offset1:204
	s_add_u32 s20, s12, s20
	s_waitcnt lgkmcnt(2)
	v_mfma_f32_16x16x32_bf16 v[164:167], v[206:209], v[210:213], v[172:175]
	v_add_u32_e32 v206, 0x3200, v196
	v_add_u32_e32 v207, 0x3400, v196
	s_addc_u32 s21, s13, 0
	v_mfma_f32_16x16x32_bf16 v[176:179], v[202:205], v[210:213], v[176:179]
	s_nop 3
	ds_write2_b32 v206, v164, v165 offset0:64 offset1:132
	v_lshl_add_u64 v[164:165], s[8:9], 0, v[128:129]
	v_add_u32_e32 v205, 0x2400, v196
	ds_write2_b32 v207, v166, v167 offset0:72 offset1:140
	v_lshlrev_b64 v[164:165], 12, v[164:165]
	v_lshl_add_u64 v[166:167], v[144:145], 1, s[20:21]
	v_add_u32_e32 v202, 0x1000, v196
	v_add_u32_e32 v203, 0x1200, v196
	v_add_u32_e32 v204, 0x2000, v196
	ds_write2_b32 v205, v178, v179 offset0:8 offset1:76
	v_lshl_add_u64 v[164:165], v[152:153], 0, v[164:165]
	v_lshl_add_u64 v[178:179], v[166:167], 0, v[130:131]
	ds_write2_b32 v202, v168, v169 offset0:64 offset1:132
	ds_write2_b32 v203, v170, v171 offset0:72 offset1:140
	ds_write2_b32 v204, v176, v177 offset0:128 offset1:196
	s_waitcnt lgkmcnt(0)
	s_barrier
	v_add_u32_e32 v208, v186, v180
	s_waitcnt vmcnt(20)
	ds_write_b128 v208, v[16:19]
	v_lshl_add_u64 v[16:17], s[8:9], 0, v[134:135]
	v_lshlrev_b64 v[166:167], 11, v[16:17]
	v_lshl_add_u64 v[16:17], v[132:133], 0, v[166:167]
	global_load_dwordx4 v[16:19], v[16:17], off
	ds_read_b64_tr_b16 v[168:169], v197 offset:33792
	ds_read_b64_tr_b16 v[170:171], v197 offset:35968
	ds_read_b64_tr_b16 v[172:173], v197 offset:51200
	ds_read_b64_tr_b16 v[174:175], v197 offset:53376
	v_mov_b32_e32 v149, v148
	v_pk_mul_f32 v[90:91], v[148:149], v[90:91]
	v_pk_mul_f32 v[88:89], v[154:155], v[88:89]
	s_waitcnt lgkmcnt(2)
	s_nop 0
	v_mfma_f32_16x16x32_bf16 v[88:91], v[168:171], v[124:127], v[88:91]
	s_waitcnt lgkmcnt(0)
	v_mfma_f32_16x16x32_bf16 v[88:91], v[172:175], v[120:123], v[88:91]
	v_add_u32_e32 v209, v186, v181
	s_waitcnt vmcnt(20)
	ds_write_b128 v209, v[20:23]
	v_lshl_add_u64 v[20:21], s[8:9], 0, v[136:137]
	v_lshlrev_b64 v[172:173], 11, v[20:21]
	v_lshl_add_u64 v[20:21], v[132:133], 0, v[172:173]
	global_load_dwordx4 v[20:23], v[20:21], off
	ds_read_b64_tr_b16 v[168:169], v197 offset:33824
	ds_read_b64_tr_b16 v[170:171], v197 offset:36000
	ds_read_b64_tr_b16 v[174:175], v197 offset:51232
	ds_read_b64_tr_b16 v[176:177], v197 offset:53408
	v_pk_mul_f32 v[94:95], v[148:149], v[94:95]
	v_pk_mul_f32 v[92:93], v[154:155], v[92:93]
	s_waitcnt lgkmcnt(2)
	s_nop 0
	v_mfma_f32_16x16x32_bf16 v[92:95], v[168:171], v[124:127], v[92:95]
	s_waitcnt lgkmcnt(0)
	v_mfma_f32_16x16x32_bf16 v[92:95], v[174:177], v[120:123], v[92:95]
	v_add_u32_e32 v210, v186, v182
	s_waitcnt vmcnt(20)
	ds_write_b128 v210, v[24:27]
	v_lshl_add_u64 v[24:25], s[8:9], 0, v[138:139]
	v_lshlrev_b64 v[170:171], 11, v[24:25]
	v_lshl_add_u64 v[24:25], v[132:133], 0, v[170:171]
	global_load_dwordx4 v[24:27], v[24:25], off
	ds_read_b64_tr_b16 v[174:175], v197 offset:33856
	ds_read_b64_tr_b16 v[176:177], v197 offset:36032
	ds_read_b64_tr_b16 v[212:213], v197 offset:51264
	ds_read_b64_tr_b16 v[214:215], v197 offset:53440
	v_pk_mul_f32 v[98:99], v[148:149], v[98:99]
	v_pk_mul_f32 v[96:97], v[154:155], v[96:97]
	s_waitcnt lgkmcnt(2)
	s_nop 0
	v_mfma_f32_16x16x32_bf16 v[96:99], v[174:177], v[124:127], v[96:99]
	s_waitcnt lgkmcnt(0)
	v_mfma_f32_16x16x32_bf16 v[96:99], v[212:215], v[120:123], v[96:99]
	v_add_u32_e32 v211, v186, v183
	s_waitcnt vmcnt(20)
	ds_write_b128 v211, v[28:31]
	v_lshl_add_u64 v[28:29], s[8:9], 0, v[140:141]
	v_lshlrev_b64 v[168:169], 11, v[28:29]
	v_lshl_add_u64 v[28:29], v[132:133], 0, v[168:169]
	global_load_dwordx4 v[28:31], v[28:29], off
	ds_read_b64_tr_b16 v[174:175], v197 offset:33888
	ds_read_b64_tr_b16 v[176:177], v197 offset:36064
	ds_read_b64_tr_b16 v[212:213], v197 offset:51296
	ds_read_b64_tr_b16 v[214:215], v197 offset:53472
	v_pk_mul_f32 v[102:103], v[148:149], v[102:103]
	v_pk_mul_f32 v[100:101], v[154:155], v[100:101]
	s_waitcnt lgkmcnt(2)
	s_nop 0
	v_mfma_f32_16x16x32_bf16 v[100:103], v[174:177], v[124:127], v[100:103]
	s_waitcnt lgkmcnt(0)
	v_mfma_f32_16x16x32_bf16 v[100:103], v[212:215], v[120:123], v[100:103]
	s_waitcnt vmcnt(20)
	ds_write_b128 v184, v[36:39]
	global_load_dwordx4 v[36:39], v[164:165], off
	ds_read_b64_tr_b16 v[174:175], v198 offset:33792
	ds_read_b64_tr_b16 v[176:177], v198 offset:35968
	ds_read_b64_tr_b16 v[212:213], v198 offset:51200
	ds_read_b64_tr_b16 v[214:215], v198 offset:53376
	v_pk_mul_f32 v[106:107], v[148:149], v[106:107]
	v_pk_mul_f32 v[104:105], v[154:155], v[104:105]
	s_waitcnt lgkmcnt(2)
	s_nop 0
	v_mfma_f32_16x16x32_bf16 v[104:107], v[174:177], v[124:127], v[104:107]
	s_waitcnt lgkmcnt(0)
	v_mfma_f32_16x16x32_bf16 v[104:107], v[212:215], v[120:123], v[104:107]
	s_waitcnt vmcnt(20)
	ds_write_b128 v185, v[40:43]
	v_add_co_u32_e32 v40, vcc, s23, v178
	s_nop 1
	v_addc_co_u32_e32 v41, vcc, 0, v179, vcc
	global_load_dwordx4 v[40:43], v[40:41], off
	ds_read_b64_tr_b16 v[174:175], v199 offset:33792
	ds_read_b64_tr_b16 v[176:177], v199 offset:35968
	ds_read_b64_tr_b16 v[212:213], v199 offset:51200
	ds_read_b64_tr_b16 v[214:215], v199 offset:53376
	v_pk_mul_f32 v[118:119], v[148:149], v[118:119]
	v_pk_mul_f32 v[116:117], v[154:155], v[116:117]
	v_pk_mul_f32 v[110:111], v[148:149], v[110:111]
	v_pk_mul_f32 v[108:109], v[154:155], v[108:109]
	s_waitcnt lgkmcnt(2)
	v_mfma_f32_16x16x32_bf16 v[116:119], v[174:177], v[124:127], v[116:119]
	ds_read_b64_tr_b16 v[174:175], v200 offset:33792
	ds_read_b64_tr_b16 v[176:177], v200 offset:35968
	v_pk_mul_f32 v[114:115], v[148:149], v[114:115]
	v_pk_mul_f32 v[112:113], v[154:155], v[112:113]
	s_waitcnt lgkmcnt(2)
	v_mfma_f32_16x16x32_bf16 v[116:119], v[212:215], v[120:123], v[116:119]
	ds_read_b64_tr_b16 v[212:213], v200 offset:51200
	ds_read_b64_tr_b16 v[214:215], v200 offset:53376
	s_waitcnt lgkmcnt(2)
	v_mfma_f32_16x16x32_bf16 v[108:111], v[174:177], v[124:127], v[108:111]
	s_waitcnt lgkmcnt(0)
	v_mfma_f32_16x16x32_bf16 v[108:111], v[212:215], v[120:123], v[108:111]
	ds_read_b128 v[174:177], v188
	ds_read_b128 v[212:215], v188 offset:16
	ds_read_b128 v[216:219], v187
	ds_read_b128 v[220:223], v187 offset:16
	ds_read_b64_tr_b16 v[224:225], v201 offset:33792
	ds_read_b64_tr_b16 v[226:227], v201 offset:35968
	s_waitcnt lgkmcnt(3)
	v_pk_add_f32 v[164:165], v[176:177], v[218:219]
	v_pk_add_f32 v[176:177], v[174:175], v[216:217]
	v_pk_mul_f32 v[174:175], v[156:157], v[164:165]
	v_pk_mul_f32 v[178:179], v[142:143], v[176:177]
	s_waitcnt lgkmcnt(2)
	v_pk_add_f32 v[176:177], v[212:213], v[220:221]
	v_mul_f32_e32 v212, v179, v179
	v_mul_f32_e32 v213, v175, v175
	v_pk_mul_f32 v[176:177], v[142:143], v[176:177]
	v_fmac_f32_e32 v212, v178, v178
	v_fmac_f32_e32 v213, v174, v174
	v_pk_add_f32 v[164:165], v[214:215], v[222:223]
	v_add_f32_e32 v212, v212, v213
	v_mul_f32_e32 v213, v177, v177
	v_pk_mul_f32 v[164:165], v[156:157], v[164:165]
	v_fmac_f32_e32 v213, v176, v176
	v_add_f32_e32 v212, v213, v212
	v_mul_f32_e32 v213, v165, v165
	v_fmac_f32_e32 v213, v164, v164
	v_add_f32_e32 v216, v213, v212
	s_waitcnt lgkmcnt(0)
	v_mfma_f32_16x16x32_bf16 v[112:115], v[224:227], v[124:127], v[112:115]
	ds_read_b64_tr_b16 v[212:213], v201 offset:51200
	ds_read_b64_tr_b16 v[214:215], v201 offset:53376
	v_add_f32_dpp v124, v216, v216 quad_perm:[1,0,3,2] row_mask:0xf bank_mask:0xf
	s_nop 1
	v_add_f32_dpp v124, v124, v124 quad_perm:[2,3,0,1] row_mask:0xf bank_mask:0xf
	s_waitcnt lgkmcnt(0)
	v_mfma_f32_16x16x32_bf16 v[112:115], v[212:215], v[120:123], v[112:115]
	s_nop 1
	v_add_f32_dpp v125, v124, v124 row_half_mirror row_mask:0xf bank_mask:0xf
	s_and_saveexec_b64 s[20:21], s[6:7]
	s_cbranch_execz .LBB0_619
	v_lshl_add_u64 v[120:121], s[14:15], 0, v[160:161]
	v_add_co_u32_e32 v120, vcc, 0x4200000, v120
	s_waitcnt lgkmcnt(0)
	v_mov_b32_e32 v122, v125
	v_addc_co_u32_e32 v121, vcc, 0, v121, vcc
	global_store_dword v[120:121], v122, off
.LBB0_619:
	s_or_b64 exec, exec, s[20:21]
	v_lshlrev_b32_e32 v120, 16, v32
	v_and_b32_e32 v121, 0xffff0000, v32
	v_pk_mul_f32 v[120:121], v[178:179], v[120:121]
	s_add_i32 s8, s22, -1
	v_cvt_pk_bf16_f32 v32, v120, v121
	v_lshlrev_b32_e32 v120, 16, v33
	v_and_b32_e32 v121, 0xffff0000, v33
	v_pk_mul_f32 v[120:121], v[174:175], v[120:121]
	s_cmp_lt_u32 s27, 62
	v_cvt_pk_bf16_f32 v33, v120, v121
	v_lshlrev_b32_e32 v120, 16, v34
	v_and_b32_e32 v121, 0xffff0000, v34
	v_pk_mul_f32 v[120:121], v[176:177], v[120:121]
	s_cselect_b32 s8, s8, s27
	v_cvt_pk_bf16_f32 v34, v120, v121
	v_lshlrev_b32_e32 v120, 16, v35
	v_and_b32_e32 v121, 0xffff0000, v35
	v_pk_mul_f32 v[120:121], v[164:165], v[120:121]
	v_lshl_add_u64 v[164:165], s[14:15], 0, v[162:163]
	v_cvt_pk_bf16_f32 v35, v120, v121
	v_add_co_u32_e32 v120, vcc, s24, v164
	s_lshl_b32 s8, s8, 6
	s_nop 0
	v_addc_co_u32_e32 v121, vcc, 0, v165, vcc
	global_store_dwordx4 v[120:121], v[32:35], off
	s_nop 1
	v_lshl_add_u64 v[32:33], s[8:9], 0, v[128:129]
	v_lshlrev_b64 v[32:33], 12, v[32:33]
	v_lshl_add_u64 v[32:33], v[158:159], 0, v[32:33]
	global_load_dwordx4 v[32:35], v[32:33], off
	s_waitcnt lgkmcnt(0)
	s_barrier
	ds_read_b128 v[174:177], v190
	ds_read_b64_tr_b16 v[126:127], v189 offset:576
	ds_read_b64_tr_b16 v[122:123], v189 offset:5184
	ds_read_b64_tr_b16 v[124:125], v189
	ds_read_b64_tr_b16 v[120:121], v189 offset:4608
	ds_read_b128 v[212:215], v190 offset:2304
	ds_read_b128 v[220:223], v190 offset:4608
	ds_read_b128 v[224:227], v190 offset:6912
	s_waitcnt lgkmcnt(5)
	v_cndmask_b32_e64 v219, v123, v127, s[4:5]
	v_cndmask_b32_e64 v218, v122, v126, s[4:5]
	s_waitcnt lgkmcnt(3)
	v_cndmask_b32_e64 v217, v121, v125, s[4:5]
	v_cndmask_b32_e64 v216, v120, v124, s[4:5]
	s_nop 1
	v_mfma_f32_16x16x32_bf16 v[174:177], v[174:177], v[216:219], 0
	s_waitcnt lgkmcnt(2)
	v_mfma_f32_16x16x32_bf16 v[212:215], v[212:215], v[216:219], 0
	s_waitcnt lgkmcnt(1)
	v_mfma_f32_16x16x32_bf16 v[220:223], v[220:223], v[216:219], 0
	s_waitcnt lgkmcnt(0)
	v_mfma_f32_16x16x32_bf16 v[216:219], v[224:227], v[216:219], 0
	s_waitcnt vmcnt(22)
	ds_write_b128 v191, v[44:47] offset:33792
	v_lshl_add_u64 v[44:45], v[146:147], 0, v[166:167]
	global_load_dwordx4 v[44:47], v[44:45], off
	ds_read_b128 v[224:227], v192
	ds_read_b128 v[228:231], v192 offset:8448
	v_cvt_pk_bf16_f32 v232, v88, v89
	v_cvt_pk_bf16_f32 v233, v90, v91
	v_cvt_pk_bf16_f32 v234, v92, v93
	v_cvt_pk_bf16_f32 v235, v94, v95
	s_waitcnt lgkmcnt(1)
	s_nop 0
	v_mfma_f32_16x16x32_bf16 v[174:177], v[224:227], v[232:235], v[174:177]
	ds_read_b128 v[224:227], v192 offset:16896
	s_waitcnt lgkmcnt(1)
	v_mfma_f32_16x16x32_bf16 v[212:215], v[228:231], v[232:235], v[212:215]
	ds_read_b128 v[228:231], v192 offset:25344
	s_waitcnt lgkmcnt(1)
	v_mfma_f32_16x16x32_bf16 v[220:223], v[224:227], v[232:235], v[220:223]
	s_waitcnt lgkmcnt(0)
	v_mfma_f32_16x16x32_bf16 v[216:219], v[228:231], v[232:235], v[216:219]
	s_waitcnt vmcnt(22)
	ds_write_b128 v193, v[48:51] offset:33792
	v_lshl_add_u64 v[48:49], v[146:147], 0, v[172:173]
	global_load_dwordx4 v[48:51], v[48:49], off
	ds_read_b128 v[224:227], v192 offset:64
	ds_read_b128 v[228:231], v192 offset:8512
	v_cvt_pk_bf16_f32 v232, v96, v97
	v_cvt_pk_bf16_f32 v233, v98, v99
	v_cvt_pk_bf16_f32 v234, v100, v101
	v_cvt_pk_bf16_f32 v235, v102, v103
	s_waitcnt lgkmcnt(1)
	s_nop 0
	v_mfma_f32_16x16x32_bf16 v[172:175], v[224:227], v[232:235], v[174:177]
	ds_read_b128 v[224:227], v192 offset:25408
	s_nop 1
	ds_read_b128 v[176:179], v192 offset:16960
	s_waitcnt lgkmcnt(2)
	v_mfma_f32_16x16x32_bf16 v[212:215], v[228:231], v[232:235], v[212:215]
	s_waitcnt lgkmcnt(0)
	v_mfma_f32_16x16x32_bf16 v[176:179], v[176:179], v[232:235], v[220:223]
	v_mfma_f32_16x16x32_bf16 v[216:219], v[224:227], v[232:235], v[216:219]
	s_waitcnt vmcnt(22)
	ds_write_b128 v194, v[52:55] offset:33792
	v_lshl_add_u64 v[52:53], v[146:147], 0, v[170:171]
	global_load_dwordx4 v[52:55], v[52:53], off
	ds_read_b128 v[220:223], v192 offset:128
	ds_read_b128 v[224:227], v192 offset:8576
	v_cvt_pk_bf16_f32 v228, v104, v105
	v_cvt_pk_bf16_f32 v229, v106, v107
	v_cvt_pk_bf16_f32 v230, v116, v117
	v_cvt_pk_bf16_f32 v231, v118, v119
	s_waitcnt lgkmcnt(1)
	s_nop 0
	v_mfma_f32_16x16x32_bf16 v[170:173], v[220:223], v[228:231], v[172:175]
	ds_read_b128 v[220:223], v192 offset:17024
	s_waitcnt lgkmcnt(1)
	v_mfma_f32_16x16x32_bf16 v[212:215], v[224:227], v[228:231], v[212:215]
	ds_read_b128 v[224:227], v192 offset:25472
	s_waitcnt lgkmcnt(1)
	v_mfma_f32_16x16x32_bf16 v[174:177], v[220:223], v[228:231], v[176:179]
	s_waitcnt lgkmcnt(0)
	v_mfma_f32_16x16x32_bf16 v[216:219], v[224:227], v[228:231], v[216:219]
	s_waitcnt vmcnt(22)
	ds_write_b128 v195, v[56:59] offset:33792
	v_lshl_add_u64 v[56:57], v[146:147], 0, v[168:169]
	global_load_dwordx4 v[56:59], v[56:57], off
	ds_read_b128 v[166:169], v192 offset:192
	ds_read_b128 v[220:223], v192 offset:8640
	v_cvt_pk_bf16_f32 v224, v108, v109
	v_cvt_pk_bf16_f32 v225, v110, v111
	v_cvt_pk_bf16_f32 v226, v112, v113
	v_cvt_pk_bf16_f32 v227, v114, v115
	s_min_u32 s20, s27, 59
	s_lshl_b32 s8, s20, 6
	s_waitcnt lgkmcnt(1)
	v_mfma_f32_16x16x32_bf16 v[166:169], v[166:169], v[224:227], v[170:173]
	s_addk_i32 s8, 0x100
	s_lshl_b32 s20, s20, 13
	s_add_u32 s20, s12, s20
	ds_read_b128 v[170:173], v192 offset:17088
	s_waitcnt lgkmcnt(1)
	v_mfma_f32_16x16x32_bf16 v[212:215], v[220:223], v[224:227], v[212:215]
	ds_read_b128 v[220:223], v192 offset:25536
	s_nop 0
	ds_write2_b32 v196, v166, v167 offset1:68
	ds_write2_b32 v196, v168, v169 offset0:136 offset1:204
	s_nop 3
	ds_write2_b32 v202, v212, v213 offset0:64 offset1:132
	s_addc_u32 s21, s13, 0
	s_waitcnt lgkmcnt(4)
	v_mfma_f32_16x16x32_bf16 v[170:173], v[170:173], v[224:227], v[174:177]
	s_waitcnt lgkmcnt(3)
	v_mfma_f32_16x16x32_bf16 v[166:169], v[220:223], v[224:227], v[216:219]
	ds_write2_b32 v203, v214, v215 offset0:72 offset1:140
	s_nop 4
	ds_write2_b32 v204, v170, v171 offset0:128 offset1:196
	ds_write2_b32 v205, v172, v173 offset0:8 offset1:76
	ds_write2_b32 v206, v166, v167 offset0:64 offset1:132
	ds_write2_b32 v207, v168, v169 offset0:72 offset1:140
	v_lshl_add_u64 v[166:167], s[8:9], 0, v[128:129]
	v_lshlrev_b64 v[166:167], 12, v[166:167]
	v_lshl_add_u64 v[174:175], v[152:153], 0, v[166:167]
	v_lshl_add_u64 v[166:167], v[144:145], 1, s[20:21]
	s_waitcnt lgkmcnt(0)
	s_barrier
	v_lshl_add_u64 v[176:177], v[166:167], 0, v[130:131]
	s_waitcnt vmcnt(21)
	ds_write_b128 v208, v[60:63]
	v_lshl_add_u64 v[60:61], s[8:9], 0, v[134:135]
	v_lshlrev_b64 v[60:61], 11, v[60:61]
	v_lshl_add_u64 v[60:61], v[132:133], 0, v[60:61]
	global_load_dwordx4 v[60:63], v[60:61], off
	ds_read_b64_tr_b16 v[166:167], v197 offset:33792
	ds_read_b64_tr_b16 v[168:169], v197 offset:35968
	ds_read_b64_tr_b16 v[170:171], v197 offset:51200
	ds_read_b64_tr_b16 v[172:173], v197 offset:53376
	v_pk_mul_f32 v[90:91], v[148:149], v[90:91]
	v_pk_mul_f32 v[88:89], v[154:155], v[88:89]
	s_waitcnt lgkmcnt(2)
	s_nop 0
	v_mfma_f32_16x16x32_bf16 v[88:91], v[166:169], v[124:127], v[88:91]
	s_waitcnt lgkmcnt(0)
	v_mfma_f32_16x16x32_bf16 v[88:91], v[170:173], v[120:123], v[88:91]
	s_waitcnt vmcnt(21)
	ds_write_b128 v209, v[64:67]
	v_lshl_add_u64 v[64:65], s[8:9], 0, v[136:137]
	v_lshlrev_b64 v[64:65], 11, v[64:65]
	v_lshl_add_u64 v[64:65], v[132:133], 0, v[64:65]
	global_load_dwordx4 v[64:67], v[64:65], off
	ds_read_b64_tr_b16 v[166:167], v197 offset:33824
	ds_read_b64_tr_b16 v[168:169], v197 offset:36000
	ds_read_b64_tr_b16 v[170:171], v197 offset:51232
	ds_read_b64_tr_b16 v[172:173], v197 offset:53408
	v_pk_mul_f32 v[94:95], v[148:149], v[94:95]
	v_pk_mul_f32 v[92:93], v[154:155], v[92:93]
	s_waitcnt lgkmcnt(2)
	s_nop 0
	v_mfma_f32_16x16x32_bf16 v[92:95], v[166:169], v[124:127], v[92:95]
	s_waitcnt lgkmcnt(0)
	v_mfma_f32_16x16x32_bf16 v[92:95], v[170:173], v[120:123], v[92:95]
	s_waitcnt vmcnt(21)
	ds_write_b128 v210, v[68:71]
	v_lshl_add_u64 v[68:69], s[8:9], 0, v[138:139]
	v_lshlrev_b64 v[68:69], 11, v[68:69]
	v_lshl_add_u64 v[68:69], v[132:133], 0, v[68:69]
	global_load_dwordx4 v[68:71], v[68:69], off
	ds_read_b64_tr_b16 v[166:167], v197 offset:33856
	ds_read_b64_tr_b16 v[168:169], v197 offset:36032
	ds_read_b64_tr_b16 v[170:171], v197 offset:51264
	ds_read_b64_tr_b16 v[172:173], v197 offset:53440
	v_pk_mul_f32 v[98:99], v[148:149], v[98:99]
	v_pk_mul_f32 v[96:97], v[154:155], v[96:97]
	s_waitcnt lgkmcnt(2)
	s_nop 0
	v_mfma_f32_16x16x32_bf16 v[96:99], v[166:169], v[124:127], v[96:99]
	s_waitcnt lgkmcnt(0)
	v_mfma_f32_16x16x32_bf16 v[96:99], v[170:173], v[120:123], v[96:99]
	s_waitcnt vmcnt(21)
	ds_write_b128 v211, v[76:79]
	v_lshl_add_u64 v[76:77], s[8:9], 0, v[140:141]
	v_lshlrev_b64 v[76:77], 11, v[76:77]
	v_lshl_add_u64 v[76:77], v[132:133], 0, v[76:77]
	global_load_dwordx4 v[76:79], v[76:77], off
	ds_read_b64_tr_b16 v[166:167], v197 offset:33888
	ds_read_b64_tr_b16 v[168:169], v197 offset:36064
	ds_read_b64_tr_b16 v[170:171], v197 offset:51296
	ds_read_b64_tr_b16 v[172:173], v197 offset:53472
	v_pk_mul_f32 v[102:103], v[148:149], v[102:103]
	v_pk_mul_f32 v[100:101], v[154:155], v[100:101]
	s_waitcnt lgkmcnt(2)
	s_nop 0
	v_mfma_f32_16x16x32_bf16 v[100:103], v[166:169], v[124:127], v[100:103]
	s_waitcnt lgkmcnt(0)
	v_mfma_f32_16x16x32_bf16 v[100:103], v[170:173], v[120:123], v[100:103]
	s_waitcnt vmcnt(21)
	ds_write_b128 v184, v[80:83]
	global_load_dwordx4 v[80:83], v[174:175], off
	ds_read_b64_tr_b16 v[166:167], v198 offset:33792
	ds_read_b64_tr_b16 v[168:169], v198 offset:35968
	ds_read_b64_tr_b16 v[170:171], v198 offset:51200
	ds_read_b64_tr_b16 v[172:173], v198 offset:53376
	v_pk_mul_f32 v[106:107], v[148:149], v[106:107]
	v_pk_mul_f32 v[104:105], v[154:155], v[104:105]
	s_waitcnt lgkmcnt(2)
	s_nop 0
	v_mfma_f32_16x16x32_bf16 v[104:107], v[166:169], v[124:127], v[104:107]
	s_waitcnt lgkmcnt(0)
	v_mfma_f32_16x16x32_bf16 v[104:107], v[170:173], v[120:123], v[104:107]
	s_waitcnt vmcnt(21)
	ds_write_b128 v185, v[84:87]
	v_add_co_u32_e32 v84, vcc, s25, v176
	s_nop 1
	v_addc_co_u32_e32 v85, vcc, 0, v177, vcc
	global_load_dwordx4 v[84:87], v[84:85], off
	ds_read_b64_tr_b16 v[166:167], v199 offset:33792
	ds_read_b64_tr_b16 v[168:169], v199 offset:35968
	ds_read_b64_tr_b16 v[170:171], v199 offset:51200
	ds_read_b64_tr_b16 v[172:173], v199 offset:53376
	v_pk_mul_f32 v[118:119], v[148:149], v[118:119]
	v_pk_mul_f32 v[116:117], v[154:155], v[116:117]
	v_pk_mul_f32 v[110:111], v[148:149], v[110:111]
	v_pk_mul_f32 v[108:109], v[154:155], v[108:109]
	s_waitcnt lgkmcnt(2)
	v_mfma_f32_16x16x32_bf16 v[116:119], v[166:169], v[124:127], v[116:119]
	ds_read_b64_tr_b16 v[166:167], v200 offset:33792
	ds_read_b64_tr_b16 v[168:169], v200 offset:35968
	v_pk_mul_f32 v[114:115], v[148:149], v[114:115]
	v_pk_mul_f32 v[112:113], v[154:155], v[112:113]
	s_waitcnt lgkmcnt(2)
	v_mfma_f32_16x16x32_bf16 v[116:119], v[170:173], v[120:123], v[116:119]
	ds_read_b64_tr_b16 v[170:171], v200 offset:51200
	ds_read_b64_tr_b16 v[172:173], v200 offset:53376
	s_waitcnt lgkmcnt(2)
	v_mfma_f32_16x16x32_bf16 v[108:111], v[166:169], v[124:127], v[108:111]
	s_waitcnt lgkmcnt(0)
	v_mfma_f32_16x16x32_bf16 v[108:111], v[170:173], v[120:123], v[108:111]
	ds_read_b128 v[166:169], v188
	ds_read_b128 v[174:177], v188 offset:16
	ds_read_b128 v[170:173], v187
	ds_read_b128 v[202:205], v187 offset:16
	ds_read_b64_tr_b16 v[206:207], v201 offset:33792
	ds_read_b64_tr_b16 v[208:209], v201 offset:35968
	s_waitcnt lgkmcnt(3)
	v_pk_add_f32 v[168:169], v[168:169], v[172:173]
	v_pk_add_f32 v[166:167], v[166:167], v[170:171]
	v_pk_mul_f32 v[168:169], v[156:157], v[168:169]
	v_pk_mul_f32 v[172:173], v[142:143], v[166:167]
	s_waitcnt lgkmcnt(2)
	v_pk_add_f32 v[170:171], v[174:175], v[202:203]
	v_mul_f32_e32 v149, v173, v173
	v_mul_f32_e32 v174, v169, v169
	v_pk_mul_f32 v[170:171], v[142:143], v[170:171]
	v_fmac_f32_e32 v149, v172, v172
	v_fmac_f32_e32 v174, v168, v168
	v_pk_add_f32 v[166:167], v[176:177], v[204:205]
	v_add_f32_e32 v149, v149, v174
	v_mul_f32_e32 v174, v171, v171
	v_pk_mul_f32 v[166:167], v[156:157], v[166:167]
	v_fmac_f32_e32 v174, v170, v170
	v_add_f32_e32 v149, v174, v149
	v_mul_f32_e32 v174, v167, v167
	v_fmac_f32_e32 v174, v166, v166
	v_add_f32_e32 v149, v174, v149
	s_waitcnt lgkmcnt(0)
	v_mfma_f32_16x16x32_bf16 v[112:115], v[206:209], v[124:127], v[112:115]
	ds_read_b64_tr_b16 v[174:175], v201 offset:51200
	ds_read_b64_tr_b16 v[176:177], v201 offset:53376
	v_add_f32_dpp v124, v149, v149 quad_perm:[1,0,3,2] row_mask:0xf bank_mask:0xf
	s_nop 1
	v_add_f32_dpp v124, v124, v124 quad_perm:[2,3,0,1] row_mask:0xf bank_mask:0xf
	s_waitcnt lgkmcnt(0)
	v_mfma_f32_16x16x32_bf16 v[112:115], v[174:177], v[120:123], v[112:115]
	s_nop 1
	v_add_f32_dpp v125, v124, v124 row_half_mirror row_mask:0xf bank_mask:0xf
	s_and_saveexec_b64 s[20:21], s[6:7]
	s_cbranch_execz .LBB0_616
	v_lshl_add_u64 v[120:121], s[14:15], 0, v[160:161]
	v_add_co_u32_e32 v120, vcc, 0x4202000, v120
	s_waitcnt lgkmcnt(0)
	v_mov_b32_e32 v122, v125
	v_addc_co_u32_e32 v121, vcc, 0, v121, vcc
	global_store_dword v[120:121], v122, off
	s_branch .LBB0_616
